# pool tiles: window sums read each LDS row once (fast path for unclipped sub-blocks); scan with coalesced LDS waits
# speedup vs baseline: 1.0257x; 1.0257x over previous
.LBB0_810:
	s_lshl_b32 s5, s4, 4
	s_add_i32 s10, s5, s33
	v_mov_b32_e32 v138, v145
	s_mov_b32 s34, 0
	v_readfirstlane_b32 s0, v0
	s_lshr_b32 s1, s0, 1
	s_sub_i32 s2, s10, s1
	s_cmp_lt_i32 s2, 0
	s_cbranch_scc1 .LBB0_812
	s_add_i32 s2, s10, s1
	s_add_i32 s2, s2, 15
	s_cmp_gt_i32 s2, s7
	s_cbranch_scc1 .LBB0_812
	s_add_i32 s2, s5, 8
	s_sub_i32 s2, s2, s1
	s_lshl_b32 s2, s2, 9
	v_add_u32_e32 v230, s2, v143
	s_cmp_eq_u32 s0, 2
	s_cbranch_scc1 .Lpool_w2
	s_cmp_eq_u32 s0, 4
	s_cbranch_scc1 .Lpool_w4
	s_cmp_eq_u32 s0, 8
	s_cbranch_scc1 .Lpool_w8
	ds_read_u16 v194, v230 offset:0
	ds_read_u16 v195, v230 offset:512
	ds_read_u16 v196, v230 offset:1024
	ds_read_u16 v197, v230 offset:1536
	ds_read_u16 v198, v230 offset:2048
	ds_read_u16 v199, v230 offset:2560
	ds_read_u16 v200, v230 offset:3072
	ds_read_u16 v201, v230 offset:3584
	ds_read_u16 v202, v230 offset:4096
	ds_read_u16 v203, v230 offset:4608
	ds_read_u16 v204, v230 offset:5120
	ds_read_u16 v205, v230 offset:5632
	ds_read_u16 v211, v230 offset:6144
	ds_read_u16 v212, v230 offset:6656
	ds_read_u16 v213, v230 offset:7168
	ds_read_u16 v214, v230 offset:7680
	ds_read_u16 v215, v230 offset:8192
	ds_read_u16 v216, v230 offset:8704
	ds_read_u16 v217, v230 offset:9216
	ds_read_u16 v218, v230 offset:9728
	ds_read_u16 v219, v230 offset:10240
	ds_read_u16 v220, v230 offset:10752
	ds_read_u16 v221, v230 offset:11264
	ds_read_u16 v222, v230 offset:11776
	ds_read_u16 v223, v230 offset:12288
	ds_read_u16 v224, v230 offset:12800
	ds_read_u16 v225, v230 offset:13312
	ds_read_u16 v226, v230 offset:13824
	ds_read_u16 v227, v230 offset:14336
	ds_read_u16 v228, v230 offset:14848
	ds_read_u16 v229, v230 offset:15360
	s_waitcnt lgkmcnt(0)
	v_lshlrev_b32_e32 v194, 16, v194
	v_lshlrev_b32_e32 v195, 16, v195
	v_lshlrev_b32_e32 v196, 16, v196
	v_lshlrev_b32_e32 v197, 16, v197
	v_lshlrev_b32_e32 v198, 16, v198
	v_lshlrev_b32_e32 v199, 16, v199
	v_lshlrev_b32_e32 v200, 16, v200
	v_lshlrev_b32_e32 v201, 16, v201
	v_lshlrev_b32_e32 v202, 16, v202
	v_lshlrev_b32_e32 v203, 16, v203
	v_lshlrev_b32_e32 v204, 16, v204
	v_lshlrev_b32_e32 v205, 16, v205
	v_lshlrev_b32_e32 v211, 16, v211
	v_lshlrev_b32_e32 v212, 16, v212
	v_lshlrev_b32_e32 v213, 16, v213
	v_lshlrev_b32_e32 v214, 16, v214
	v_lshlrev_b32_e32 v215, 16, v215
	v_lshlrev_b32_e32 v216, 16, v216
	v_lshlrev_b32_e32 v217, 16, v217
	v_lshlrev_b32_e32 v218, 16, v218
	v_lshlrev_b32_e32 v219, 16, v219
	v_lshlrev_b32_e32 v220, 16, v220
	v_lshlrev_b32_e32 v221, 16, v221
	v_lshlrev_b32_e32 v222, 16, v222
	v_lshlrev_b32_e32 v223, 16, v223
	v_lshlrev_b32_e32 v224, 16, v224
	v_lshlrev_b32_e32 v225, 16, v225
	v_lshlrev_b32_e32 v226, 16, v226
	v_lshlrev_b32_e32 v227, 16, v227
	v_lshlrev_b32_e32 v228, 16, v228
	v_lshlrev_b32_e32 v229, 16, v229
	v_add_f32_e32 v231, v194, v195
	v_add_f32_e32 v231, v231, v196
	v_add_f32_e32 v231, v231, v197
	v_add_f32_e32 v231, v231, v198
	v_add_f32_e32 v231, v231, v199
	v_add_f32_e32 v231, v231, v200
	v_add_f32_e32 v231, v231, v201
	v_add_f32_e32 v231, v231, v202
	v_add_f32_e32 v231, v231, v203
	v_add_f32_e32 v231, v231, v204
	v_add_f32_e32 v231, v231, v205
	v_add_f32_e32 v231, v231, v211
	v_add_f32_e32 v231, v231, v212
	v_add_f32_e32 v231, v231, v213
	v_add_f32_e32 v231, v231, v214
	v_mul_f32_e32 v231, 0x3d800000, v231
	v_sub_f32_e32 v231, v231, v202
	ds_write_b32 v141, v231 offset:40960
	v_add_f32_e32 v232, v195, v196
	v_add_f32_e32 v232, v232, v197
	v_add_f32_e32 v232, v232, v198
	v_add_f32_e32 v232, v232, v199
	v_add_f32_e32 v232, v232, v200
	v_add_f32_e32 v232, v232, v201
	v_add_f32_e32 v232, v232, v202
	v_add_f32_e32 v232, v232, v203
	v_add_f32_e32 v232, v232, v204
	v_add_f32_e32 v232, v232, v205
	v_add_f32_e32 v232, v232, v211
	v_add_f32_e32 v232, v232, v212
	v_add_f32_e32 v232, v232, v213
	v_add_f32_e32 v232, v232, v214
	v_add_f32_e32 v232, v232, v215
	v_mul_f32_e32 v232, 0x3d800000, v232
	v_sub_f32_e32 v232, v232, v203
	ds_write_b32 v141, v232 offset:41984
	v_add_f32_e32 v231, v196, v197
	v_add_f32_e32 v231, v231, v198
	v_add_f32_e32 v231, v231, v199
	v_add_f32_e32 v231, v231, v200
	v_add_f32_e32 v231, v231, v201
	v_add_f32_e32 v231, v231, v202
	v_add_f32_e32 v231, v231, v203
	v_add_f32_e32 v231, v231, v204
	v_add_f32_e32 v231, v231, v205
	v_add_f32_e32 v231, v231, v211
	v_add_f32_e32 v231, v231, v212
	v_add_f32_e32 v231, v231, v213
	v_add_f32_e32 v231, v231, v214
	v_add_f32_e32 v231, v231, v215
	v_add_f32_e32 v231, v231, v216
	v_mul_f32_e32 v231, 0x3d800000, v231
	v_sub_f32_e32 v231, v231, v204
	ds_write_b32 v141, v231 offset:43008
	v_add_f32_e32 v232, v197, v198
	v_add_f32_e32 v232, v232, v199
	v_add_f32_e32 v232, v232, v200
	v_add_f32_e32 v232, v232, v201
	v_add_f32_e32 v232, v232, v202
	v_add_f32_e32 v232, v232, v203
	v_add_f32_e32 v232, v232, v204
	v_add_f32_e32 v232, v232, v205
	v_add_f32_e32 v232, v232, v211
	v_add_f32_e32 v232, v232, v212
	v_add_f32_e32 v232, v232, v213
	v_add_f32_e32 v232, v232, v214
	v_add_f32_e32 v232, v232, v215
	v_add_f32_e32 v232, v232, v216
	v_add_f32_e32 v232, v232, v217
	v_mul_f32_e32 v232, 0x3d800000, v232
	v_sub_f32_e32 v232, v232, v205
	ds_write_b32 v141, v232 offset:44032
	v_add_f32_e32 v231, v198, v199
	v_add_f32_e32 v231, v231, v200
	v_add_f32_e32 v231, v231, v201
	v_add_f32_e32 v231, v231, v202
	v_add_f32_e32 v231, v231, v203
	v_add_f32_e32 v231, v231, v204
	v_add_f32_e32 v231, v231, v205
	v_add_f32_e32 v231, v231, v211
	v_add_f32_e32 v231, v231, v212
	v_add_f32_e32 v231, v231, v213
	v_add_f32_e32 v231, v231, v214
	v_add_f32_e32 v231, v231, v215
	v_add_f32_e32 v231, v231, v216
	v_add_f32_e32 v231, v231, v217
	v_add_f32_e32 v231, v231, v218
	v_mul_f32_e32 v231, 0x3d800000, v231
	v_sub_f32_e32 v231, v231, v211
	ds_write_b32 v141, v231 offset:45056
	v_add_f32_e32 v232, v199, v200
	v_add_f32_e32 v232, v232, v201
	v_add_f32_e32 v232, v232, v202
	v_add_f32_e32 v232, v232, v203
	v_add_f32_e32 v232, v232, v204
	v_add_f32_e32 v232, v232, v205
	v_add_f32_e32 v232, v232, v211
	v_add_f32_e32 v232, v232, v212
	v_add_f32_e32 v232, v232, v213
	v_add_f32_e32 v232, v232, v214
	v_add_f32_e32 v232, v232, v215
	v_add_f32_e32 v232, v232, v216
	v_add_f32_e32 v232, v232, v217
	v_add_f32_e32 v232, v232, v218
	v_add_f32_e32 v232, v232, v219
	v_mul_f32_e32 v232, 0x3d800000, v232
	v_sub_f32_e32 v232, v232, v212
	ds_write_b32 v141, v232 offset:46080
	v_add_f32_e32 v231, v200, v201
	v_add_f32_e32 v231, v231, v202
	v_add_f32_e32 v231, v231, v203
	v_add_f32_e32 v231, v231, v204
	v_add_f32_e32 v231, v231, v205
	v_add_f32_e32 v231, v231, v211
	v_add_f32_e32 v231, v231, v212
	v_add_f32_e32 v231, v231, v213
	v_add_f32_e32 v231, v231, v214
	v_add_f32_e32 v231, v231, v215
	v_add_f32_e32 v231, v231, v216
	v_add_f32_e32 v231, v231, v217
	v_add_f32_e32 v231, v231, v218
	v_add_f32_e32 v231, v231, v219
	v_add_f32_e32 v231, v231, v220
	v_mul_f32_e32 v231, 0x3d800000, v231
	v_sub_f32_e32 v231, v231, v213
	ds_write_b32 v141, v231 offset:47104
	v_add_f32_e32 v232, v201, v202
	v_add_f32_e32 v232, v232, v203
	v_add_f32_e32 v232, v232, v204
	v_add_f32_e32 v232, v232, v205
	v_add_f32_e32 v232, v232, v211
	v_add_f32_e32 v232, v232, v212
	v_add_f32_e32 v232, v232, v213
	v_add_f32_e32 v232, v232, v214
	v_add_f32_e32 v232, v232, v215
	v_add_f32_e32 v232, v232, v216
	v_add_f32_e32 v232, v232, v217
	v_add_f32_e32 v232, v232, v218
	v_add_f32_e32 v232, v232, v219
	v_add_f32_e32 v232, v232, v220
	v_add_f32_e32 v232, v232, v221
	v_mul_f32_e32 v232, 0x3d800000, v232
	v_sub_f32_e32 v232, v232, v214
	ds_write_b32 v141, v232 offset:48128
	v_add_f32_e32 v231, v202, v203
	v_add_f32_e32 v231, v231, v204
	v_add_f32_e32 v231, v231, v205
	v_add_f32_e32 v231, v231, v211
	v_add_f32_e32 v231, v231, v212
	v_add_f32_e32 v231, v231, v213
	v_add_f32_e32 v231, v231, v214
	v_add_f32_e32 v231, v231, v215
	v_add_f32_e32 v231, v231, v216
	v_add_f32_e32 v231, v231, v217
	v_add_f32_e32 v231, v231, v218
	v_add_f32_e32 v231, v231, v219
	v_add_f32_e32 v231, v231, v220
	v_add_f32_e32 v231, v231, v221
	v_add_f32_e32 v231, v231, v222
	v_mul_f32_e32 v231, 0x3d800000, v231
	v_sub_f32_e32 v231, v231, v215
	ds_write_b32 v141, v231 offset:49152
	v_add_f32_e32 v232, v203, v204
	v_add_f32_e32 v232, v232, v205
	v_add_f32_e32 v232, v232, v211
	v_add_f32_e32 v232, v232, v212
	v_add_f32_e32 v232, v232, v213
	v_add_f32_e32 v232, v232, v214
	v_add_f32_e32 v232, v232, v215
	v_add_f32_e32 v232, v232, v216
	v_add_f32_e32 v232, v232, v217
	v_add_f32_e32 v232, v232, v218
	v_add_f32_e32 v232, v232, v219
	v_add_f32_e32 v232, v232, v220
	v_add_f32_e32 v232, v232, v221
	v_add_f32_e32 v232, v232, v222
	v_add_f32_e32 v232, v232, v223
	v_mul_f32_e32 v232, 0x3d800000, v232
	v_sub_f32_e32 v232, v232, v216
	ds_write_b32 v141, v232 offset:50176
	v_add_f32_e32 v231, v204, v205
	v_add_f32_e32 v231, v231, v211
	v_add_f32_e32 v231, v231, v212
	v_add_f32_e32 v231, v231, v213
	v_add_f32_e32 v231, v231, v214
	v_add_f32_e32 v231, v231, v215
	v_add_f32_e32 v231, v231, v216
	v_add_f32_e32 v231, v231, v217
	v_add_f32_e32 v231, v231, v218
	v_add_f32_e32 v231, v231, v219
	v_add_f32_e32 v231, v231, v220
	v_add_f32_e32 v231, v231, v221
	v_add_f32_e32 v231, v231, v222
	v_add_f32_e32 v231, v231, v223
	v_add_f32_e32 v231, v231, v224
	v_mul_f32_e32 v231, 0x3d800000, v231
	v_sub_f32_e32 v231, v231, v217
	ds_write_b32 v141, v231 offset:51200
	v_add_f32_e32 v232, v205, v211
	v_add_f32_e32 v232, v232, v212
	v_add_f32_e32 v232, v232, v213
	v_add_f32_e32 v232, v232, v214
	v_add_f32_e32 v232, v232, v215
	v_add_f32_e32 v232, v232, v216
	v_add_f32_e32 v232, v232, v217
	v_add_f32_e32 v232, v232, v218
	v_add_f32_e32 v232, v232, v219
	v_add_f32_e32 v232, v232, v220
	v_add_f32_e32 v232, v232, v221
	v_add_f32_e32 v232, v232, v222
	v_add_f32_e32 v232, v232, v223
	v_add_f32_e32 v232, v232, v224
	v_add_f32_e32 v232, v232, v225
	v_mul_f32_e32 v232, 0x3d800000, v232
	v_sub_f32_e32 v232, v232, v218
	ds_write_b32 v141, v232 offset:52224
	v_add_f32_e32 v231, v211, v212
	v_add_f32_e32 v231, v231, v213
	v_add_f32_e32 v231, v231, v214
	v_add_f32_e32 v231, v231, v215
	v_add_f32_e32 v231, v231, v216
	v_add_f32_e32 v231, v231, v217
	v_add_f32_e32 v231, v231, v218
	v_add_f32_e32 v231, v231, v219
	v_add_f32_e32 v231, v231, v220
	v_add_f32_e32 v231, v231, v221
	v_add_f32_e32 v231, v231, v222
	v_add_f32_e32 v231, v231, v223
	v_add_f32_e32 v231, v231, v224
	v_add_f32_e32 v231, v231, v225
	v_add_f32_e32 v231, v231, v226
	v_mul_f32_e32 v231, 0x3d800000, v231
	v_sub_f32_e32 v231, v231, v219
	ds_write_b32 v141, v231 offset:53248
	v_add_f32_e32 v232, v212, v213
	v_add_f32_e32 v232, v232, v214
	v_add_f32_e32 v232, v232, v215
	v_add_f32_e32 v232, v232, v216
	v_add_f32_e32 v232, v232, v217
	v_add_f32_e32 v232, v232, v218
	v_add_f32_e32 v232, v232, v219
	v_add_f32_e32 v232, v232, v220
	v_add_f32_e32 v232, v232, v221
	v_add_f32_e32 v232, v232, v222
	v_add_f32_e32 v232, v232, v223
	v_add_f32_e32 v232, v232, v224
	v_add_f32_e32 v232, v232, v225
	v_add_f32_e32 v232, v232, v226
	v_add_f32_e32 v232, v232, v227
	v_mul_f32_e32 v232, 0x3d800000, v232
	v_sub_f32_e32 v232, v232, v220
	ds_write_b32 v141, v232 offset:54272
	v_add_f32_e32 v231, v213, v214
	v_add_f32_e32 v231, v231, v215
	v_add_f32_e32 v231, v231, v216
	v_add_f32_e32 v231, v231, v217
	v_add_f32_e32 v231, v231, v218
	v_add_f32_e32 v231, v231, v219
	v_add_f32_e32 v231, v231, v220
	v_add_f32_e32 v231, v231, v221
	v_add_f32_e32 v231, v231, v222
	v_add_f32_e32 v231, v231, v223
	v_add_f32_e32 v231, v231, v224
	v_add_f32_e32 v231, v231, v225
	v_add_f32_e32 v231, v231, v226
	v_add_f32_e32 v231, v231, v227
	v_add_f32_e32 v231, v231, v228
	v_mul_f32_e32 v231, 0x3d800000, v231
	v_sub_f32_e32 v231, v231, v221
	ds_write_b32 v141, v231 offset:55296
	v_add_f32_e32 v232, v214, v215
	v_add_f32_e32 v232, v232, v216
	v_add_f32_e32 v232, v232, v217
	v_add_f32_e32 v232, v232, v218
	v_add_f32_e32 v232, v232, v219
	v_add_f32_e32 v232, v232, v220
	v_add_f32_e32 v232, v232, v221
	v_add_f32_e32 v232, v232, v222
	v_add_f32_e32 v232, v232, v223
	v_add_f32_e32 v232, v232, v224
	v_add_f32_e32 v232, v232, v225
	v_add_f32_e32 v232, v232, v226
	v_add_f32_e32 v232, v232, v227
	v_add_f32_e32 v232, v232, v228
	v_add_f32_e32 v232, v232, v229
	v_mul_f32_e32 v232, 0x3d800000, v232
	v_sub_f32_e32 v232, v232, v222
	ds_write_b32 v141, v232 offset:56320
	s_branch .LBB0_816
.Lpool_w8:
	ds_read_u16 v194, v230 offset:0
	ds_read_u16 v195, v230 offset:512
	ds_read_u16 v196, v230 offset:1024
	ds_read_u16 v197, v230 offset:1536
	ds_read_u16 v198, v230 offset:2048
	ds_read_u16 v199, v230 offset:2560
	ds_read_u16 v200, v230 offset:3072
	ds_read_u16 v201, v230 offset:3584
	ds_read_u16 v202, v230 offset:4096
	ds_read_u16 v203, v230 offset:4608
	ds_read_u16 v204, v230 offset:5120
	ds_read_u16 v205, v230 offset:5632
	ds_read_u16 v211, v230 offset:6144
	ds_read_u16 v212, v230 offset:6656
	ds_read_u16 v213, v230 offset:7168
	ds_read_u16 v214, v230 offset:7680
	ds_read_u16 v215, v230 offset:8192
	ds_read_u16 v216, v230 offset:8704
	ds_read_u16 v217, v230 offset:9216
	ds_read_u16 v218, v230 offset:9728
	ds_read_u16 v219, v230 offset:10240
	ds_read_u16 v220, v230 offset:10752
	ds_read_u16 v221, v230 offset:11264
	s_waitcnt lgkmcnt(0)
	v_lshlrev_b32_e32 v194, 16, v194
	v_lshlrev_b32_e32 v195, 16, v195
	v_lshlrev_b32_e32 v196, 16, v196
	v_lshlrev_b32_e32 v197, 16, v197
	v_lshlrev_b32_e32 v198, 16, v198
	v_lshlrev_b32_e32 v199, 16, v199
	v_lshlrev_b32_e32 v200, 16, v200
	v_lshlrev_b32_e32 v201, 16, v201
	v_lshlrev_b32_e32 v202, 16, v202
	v_lshlrev_b32_e32 v203, 16, v203
	v_lshlrev_b32_e32 v204, 16, v204
	v_lshlrev_b32_e32 v205, 16, v205
	v_lshlrev_b32_e32 v211, 16, v211
	v_lshlrev_b32_e32 v212, 16, v212
	v_lshlrev_b32_e32 v213, 16, v213
	v_lshlrev_b32_e32 v214, 16, v214
	v_lshlrev_b32_e32 v215, 16, v215
	v_lshlrev_b32_e32 v216, 16, v216
	v_lshlrev_b32_e32 v217, 16, v217
	v_lshlrev_b32_e32 v218, 16, v218
	v_lshlrev_b32_e32 v219, 16, v219
	v_lshlrev_b32_e32 v220, 16, v220
	v_lshlrev_b32_e32 v221, 16, v221
	v_add_f32_e32 v231, v194, v195
	v_add_f32_e32 v231, v231, v196
	v_add_f32_e32 v231, v231, v197
	v_add_f32_e32 v231, v231, v198
	v_add_f32_e32 v231, v231, v199
	v_add_f32_e32 v231, v231, v200
	v_add_f32_e32 v231, v231, v201
	v_mul_f32_e32 v231, 0x3e000000, v231
	v_sub_f32_e32 v231, v231, v198
	ds_write_b32 v141, v231 offset:40960
	v_add_f32_e32 v232, v195, v196
	v_add_f32_e32 v232, v232, v197
	v_add_f32_e32 v232, v232, v198
	v_add_f32_e32 v232, v232, v199
	v_add_f32_e32 v232, v232, v200
	v_add_f32_e32 v232, v232, v201
	v_add_f32_e32 v232, v232, v202
	v_mul_f32_e32 v232, 0x3e000000, v232
	v_sub_f32_e32 v232, v232, v199
	ds_write_b32 v141, v232 offset:41984
	v_add_f32_e32 v231, v196, v197
	v_add_f32_e32 v231, v231, v198
	v_add_f32_e32 v231, v231, v199
	v_add_f32_e32 v231, v231, v200
	v_add_f32_e32 v231, v231, v201
	v_add_f32_e32 v231, v231, v202
	v_add_f32_e32 v231, v231, v203
	v_mul_f32_e32 v231, 0x3e000000, v231
	v_sub_f32_e32 v231, v231, v200
	ds_write_b32 v141, v231 offset:43008
	v_add_f32_e32 v232, v197, v198
	v_add_f32_e32 v232, v232, v199
	v_add_f32_e32 v232, v232, v200
	v_add_f32_e32 v232, v232, v201
	v_add_f32_e32 v232, v232, v202
	v_add_f32_e32 v232, v232, v203
	v_add_f32_e32 v232, v232, v204
	v_mul_f32_e32 v232, 0x3e000000, v232
	v_sub_f32_e32 v232, v232, v201
	ds_write_b32 v141, v232 offset:44032
	v_add_f32_e32 v231, v198, v199
	v_add_f32_e32 v231, v231, v200
	v_add_f32_e32 v231, v231, v201
	v_add_f32_e32 v231, v231, v202
	v_add_f32_e32 v231, v231, v203
	v_add_f32_e32 v231, v231, v204
	v_add_f32_e32 v231, v231, v205
	v_mul_f32_e32 v231, 0x3e000000, v231
	v_sub_f32_e32 v231, v231, v202
	ds_write_b32 v141, v231 offset:45056
	v_add_f32_e32 v232, v199, v200
	v_add_f32_e32 v232, v232, v201
	v_add_f32_e32 v232, v232, v202
	v_add_f32_e32 v232, v232, v203
	v_add_f32_e32 v232, v232, v204
	v_add_f32_e32 v232, v232, v205
	v_add_f32_e32 v232, v232, v211
	v_mul_f32_e32 v232, 0x3e000000, v232
	v_sub_f32_e32 v232, v232, v203
	ds_write_b32 v141, v232 offset:46080
	v_add_f32_e32 v231, v200, v201
	v_add_f32_e32 v231, v231, v202
	v_add_f32_e32 v231, v231, v203
	v_add_f32_e32 v231, v231, v204
	v_add_f32_e32 v231, v231, v205
	v_add_f32_e32 v231, v231, v211
	v_add_f32_e32 v231, v231, v212
	v_mul_f32_e32 v231, 0x3e000000, v231
	v_sub_f32_e32 v231, v231, v204
	ds_write_b32 v141, v231 offset:47104
	v_add_f32_e32 v232, v201, v202
	v_add_f32_e32 v232, v232, v203
	v_add_f32_e32 v232, v232, v204
	v_add_f32_e32 v232, v232, v205
	v_add_f32_e32 v232, v232, v211
	v_add_f32_e32 v232, v232, v212
	v_add_f32_e32 v232, v232, v213
	v_mul_f32_e32 v232, 0x3e000000, v232
	v_sub_f32_e32 v232, v232, v205
	ds_write_b32 v141, v232 offset:48128
	v_add_f32_e32 v231, v202, v203
	v_add_f32_e32 v231, v231, v204
	v_add_f32_e32 v231, v231, v205
	v_add_f32_e32 v231, v231, v211
	v_add_f32_e32 v231, v231, v212
	v_add_f32_e32 v231, v231, v213
	v_add_f32_e32 v231, v231, v214
	v_mul_f32_e32 v231, 0x3e000000, v231
	v_sub_f32_e32 v231, v231, v211
	ds_write_b32 v141, v231 offset:49152
	v_add_f32_e32 v232, v203, v204
	v_add_f32_e32 v232, v232, v205
	v_add_f32_e32 v232, v232, v211
	v_add_f32_e32 v232, v232, v212
	v_add_f32_e32 v232, v232, v213
	v_add_f32_e32 v232, v232, v214
	v_add_f32_e32 v232, v232, v215
	v_mul_f32_e32 v232, 0x3e000000, v232
	v_sub_f32_e32 v232, v232, v212
	ds_write_b32 v141, v232 offset:50176
	v_add_f32_e32 v231, v204, v205
	v_add_f32_e32 v231, v231, v211
	v_add_f32_e32 v231, v231, v212
	v_add_f32_e32 v231, v231, v213
	v_add_f32_e32 v231, v231, v214
	v_add_f32_e32 v231, v231, v215
	v_add_f32_e32 v231, v231, v216
	v_mul_f32_e32 v231, 0x3e000000, v231
	v_sub_f32_e32 v231, v231, v213
	ds_write_b32 v141, v231 offset:51200
	v_add_f32_e32 v232, v205, v211
	v_add_f32_e32 v232, v232, v212
	v_add_f32_e32 v232, v232, v213
	v_add_f32_e32 v232, v232, v214
	v_add_f32_e32 v232, v232, v215
	v_add_f32_e32 v232, v232, v216
	v_add_f32_e32 v232, v232, v217
	v_mul_f32_e32 v232, 0x3e000000, v232
	v_sub_f32_e32 v232, v232, v214
	ds_write_b32 v141, v232 offset:52224
	v_add_f32_e32 v231, v211, v212
	v_add_f32_e32 v231, v231, v213
	v_add_f32_e32 v231, v231, v214
	v_add_f32_e32 v231, v231, v215
	v_add_f32_e32 v231, v231, v216
	v_add_f32_e32 v231, v231, v217
	v_add_f32_e32 v231, v231, v218
	v_mul_f32_e32 v231, 0x3e000000, v231
	v_sub_f32_e32 v231, v231, v215
	ds_write_b32 v141, v231 offset:53248
	v_add_f32_e32 v232, v212, v213
	v_add_f32_e32 v232, v232, v214
	v_add_f32_e32 v232, v232, v215
	v_add_f32_e32 v232, v232, v216
	v_add_f32_e32 v232, v232, v217
	v_add_f32_e32 v232, v232, v218
	v_add_f32_e32 v232, v232, v219
	v_mul_f32_e32 v232, 0x3e000000, v232
	v_sub_f32_e32 v232, v232, v216
	ds_write_b32 v141, v232 offset:54272
	v_add_f32_e32 v231, v213, v214
	v_add_f32_e32 v231, v231, v215
	v_add_f32_e32 v231, v231, v216
	v_add_f32_e32 v231, v231, v217
	v_add_f32_e32 v231, v231, v218
	v_add_f32_e32 v231, v231, v219
	v_add_f32_e32 v231, v231, v220
	v_mul_f32_e32 v231, 0x3e000000, v231
	v_sub_f32_e32 v231, v231, v217
	ds_write_b32 v141, v231 offset:55296
	v_add_f32_e32 v232, v214, v215
	v_add_f32_e32 v232, v232, v216
	v_add_f32_e32 v232, v232, v217
	v_add_f32_e32 v232, v232, v218
	v_add_f32_e32 v232, v232, v219
	v_add_f32_e32 v232, v232, v220
	v_add_f32_e32 v232, v232, v221
	v_mul_f32_e32 v232, 0x3e000000, v232
	v_sub_f32_e32 v232, v232, v218
	ds_write_b32 v141, v232 offset:56320
	s_branch .LBB0_816
.Lpool_w4:
	ds_read_u16 v194, v230 offset:0
	ds_read_u16 v195, v230 offset:512
	ds_read_u16 v196, v230 offset:1024
	ds_read_u16 v197, v230 offset:1536
	ds_read_u16 v198, v230 offset:2048
	ds_read_u16 v199, v230 offset:2560
	ds_read_u16 v200, v230 offset:3072
	ds_read_u16 v201, v230 offset:3584
	ds_read_u16 v202, v230 offset:4096
	ds_read_u16 v203, v230 offset:4608
	ds_read_u16 v204, v230 offset:5120
	ds_read_u16 v205, v230 offset:5632
	ds_read_u16 v211, v230 offset:6144
	ds_read_u16 v212, v230 offset:6656
	ds_read_u16 v213, v230 offset:7168
	ds_read_u16 v214, v230 offset:7680
	ds_read_u16 v215, v230 offset:8192
	ds_read_u16 v216, v230 offset:8704
	ds_read_u16 v217, v230 offset:9216
	s_waitcnt lgkmcnt(0)
	v_lshlrev_b32_e32 v194, 16, v194
	v_lshlrev_b32_e32 v195, 16, v195
	v_lshlrev_b32_e32 v196, 16, v196
	v_lshlrev_b32_e32 v197, 16, v197
	v_lshlrev_b32_e32 v198, 16, v198
	v_lshlrev_b32_e32 v199, 16, v199
	v_lshlrev_b32_e32 v200, 16, v200
	v_lshlrev_b32_e32 v201, 16, v201
	v_lshlrev_b32_e32 v202, 16, v202
	v_lshlrev_b32_e32 v203, 16, v203
	v_lshlrev_b32_e32 v204, 16, v204
	v_lshlrev_b32_e32 v205, 16, v205
	v_lshlrev_b32_e32 v211, 16, v211
	v_lshlrev_b32_e32 v212, 16, v212
	v_lshlrev_b32_e32 v213, 16, v213
	v_lshlrev_b32_e32 v214, 16, v214
	v_lshlrev_b32_e32 v215, 16, v215
	v_lshlrev_b32_e32 v216, 16, v216
	v_lshlrev_b32_e32 v217, 16, v217
	v_add_f32_e32 v231, v194, v195
	v_add_f32_e32 v231, v231, v196
	v_add_f32_e32 v231, v231, v197
	v_mul_f32_e32 v231, 0x3e800000, v231
	v_sub_f32_e32 v231, v231, v196
	ds_write_b32 v141, v231 offset:40960
	v_add_f32_e32 v232, v195, v196
	v_add_f32_e32 v232, v232, v197
	v_add_f32_e32 v232, v232, v198
	v_mul_f32_e32 v232, 0x3e800000, v232
	v_sub_f32_e32 v232, v232, v197
	ds_write_b32 v141, v232 offset:41984
	v_add_f32_e32 v231, v196, v197
	v_add_f32_e32 v231, v231, v198
	v_add_f32_e32 v231, v231, v199
	v_mul_f32_e32 v231, 0x3e800000, v231
	v_sub_f32_e32 v231, v231, v198
	ds_write_b32 v141, v231 offset:43008
	v_add_f32_e32 v232, v197, v198
	v_add_f32_e32 v232, v232, v199
	v_add_f32_e32 v232, v232, v200
	v_mul_f32_e32 v232, 0x3e800000, v232
	v_sub_f32_e32 v232, v232, v199
	ds_write_b32 v141, v232 offset:44032
	v_add_f32_e32 v231, v198, v199
	v_add_f32_e32 v231, v231, v200
	v_add_f32_e32 v231, v231, v201
	v_mul_f32_e32 v231, 0x3e800000, v231
	v_sub_f32_e32 v231, v231, v200
	ds_write_b32 v141, v231 offset:45056
	v_add_f32_e32 v232, v199, v200
	v_add_f32_e32 v232, v232, v201
	v_add_f32_e32 v232, v232, v202
	v_mul_f32_e32 v232, 0x3e800000, v232
	v_sub_f32_e32 v232, v232, v201
	ds_write_b32 v141, v232 offset:46080
	v_add_f32_e32 v231, v200, v201
	v_add_f32_e32 v231, v231, v202
	v_add_f32_e32 v231, v231, v203
	v_mul_f32_e32 v231, 0x3e800000, v231
	v_sub_f32_e32 v231, v231, v202
	ds_write_b32 v141, v231 offset:47104
	v_add_f32_e32 v232, v201, v202
	v_add_f32_e32 v232, v232, v203
	v_add_f32_e32 v232, v232, v204
	v_mul_f32_e32 v232, 0x3e800000, v232
	v_sub_f32_e32 v232, v232, v203
	ds_write_b32 v141, v232 offset:48128
	v_add_f32_e32 v231, v202, v203
	v_add_f32_e32 v231, v231, v204
	v_add_f32_e32 v231, v231, v205
	v_mul_f32_e32 v231, 0x3e800000, v231
	v_sub_f32_e32 v231, v231, v204
	ds_write_b32 v141, v231 offset:49152
	v_add_f32_e32 v232, v203, v204
	v_add_f32_e32 v232, v232, v205
	v_add_f32_e32 v232, v232, v211
	v_mul_f32_e32 v232, 0x3e800000, v232
	v_sub_f32_e32 v232, v232, v205
	ds_write_b32 v141, v232 offset:50176
	v_add_f32_e32 v231, v204, v205
	v_add_f32_e32 v231, v231, v211
	v_add_f32_e32 v231, v231, v212
	v_mul_f32_e32 v231, 0x3e800000, v231
	v_sub_f32_e32 v231, v231, v211
	ds_write_b32 v141, v231 offset:51200
	v_add_f32_e32 v232, v205, v211
	v_add_f32_e32 v232, v232, v212
	v_add_f32_e32 v232, v232, v213
	v_mul_f32_e32 v232, 0x3e800000, v232
	v_sub_f32_e32 v232, v232, v212
	ds_write_b32 v141, v232 offset:52224
	v_add_f32_e32 v231, v211, v212
	v_add_f32_e32 v231, v231, v213
	v_add_f32_e32 v231, v231, v214
	v_mul_f32_e32 v231, 0x3e800000, v231
	v_sub_f32_e32 v231, v231, v213
	ds_write_b32 v141, v231 offset:53248
	v_add_f32_e32 v232, v212, v213
	v_add_f32_e32 v232, v232, v214
	v_add_f32_e32 v232, v232, v215
	v_mul_f32_e32 v232, 0x3e800000, v232
	v_sub_f32_e32 v232, v232, v214
	ds_write_b32 v141, v232 offset:54272
	v_add_f32_e32 v231, v213, v214
	v_add_f32_e32 v231, v231, v215
	v_add_f32_e32 v231, v231, v216
	v_mul_f32_e32 v231, 0x3e800000, v231
	v_sub_f32_e32 v231, v231, v215
	ds_write_b32 v141, v231 offset:55296
	v_add_f32_e32 v232, v214, v215
	v_add_f32_e32 v232, v232, v216
	v_add_f32_e32 v232, v232, v217
	v_mul_f32_e32 v232, 0x3e800000, v232
	v_sub_f32_e32 v232, v232, v216
	ds_write_b32 v141, v232 offset:56320
	s_branch .LBB0_816
.Lpool_w2:
	ds_read_u16 v194, v230 offset:0
	ds_read_u16 v195, v230 offset:512
	ds_read_u16 v196, v230 offset:1024
	ds_read_u16 v197, v230 offset:1536
	ds_read_u16 v198, v230 offset:2048
	ds_read_u16 v199, v230 offset:2560
	ds_read_u16 v200, v230 offset:3072
	ds_read_u16 v201, v230 offset:3584
	ds_read_u16 v202, v230 offset:4096
	ds_read_u16 v203, v230 offset:4608
	ds_read_u16 v204, v230 offset:5120
	ds_read_u16 v205, v230 offset:5632
	ds_read_u16 v211, v230 offset:6144
	ds_read_u16 v212, v230 offset:6656
	ds_read_u16 v213, v230 offset:7168
	ds_read_u16 v214, v230 offset:7680
	ds_read_u16 v215, v230 offset:8192
	s_waitcnt lgkmcnt(0)
	v_lshlrev_b32_e32 v194, 16, v194
	v_lshlrev_b32_e32 v195, 16, v195
	v_lshlrev_b32_e32 v196, 16, v196
	v_lshlrev_b32_e32 v197, 16, v197
	v_lshlrev_b32_e32 v198, 16, v198
	v_lshlrev_b32_e32 v199, 16, v199
	v_lshlrev_b32_e32 v200, 16, v200
	v_lshlrev_b32_e32 v201, 16, v201
	v_lshlrev_b32_e32 v202, 16, v202
	v_lshlrev_b32_e32 v203, 16, v203
	v_lshlrev_b32_e32 v204, 16, v204
	v_lshlrev_b32_e32 v205, 16, v205
	v_lshlrev_b32_e32 v211, 16, v211
	v_lshlrev_b32_e32 v212, 16, v212
	v_lshlrev_b32_e32 v213, 16, v213
	v_lshlrev_b32_e32 v214, 16, v214
	v_lshlrev_b32_e32 v215, 16, v215
	v_add_f32_e32 v231, v194, v195
	v_mul_f32_e32 v231, 0.5, v231
	v_sub_f32_e32 v231, v231, v195
	ds_write_b32 v141, v231 offset:40960
	v_add_f32_e32 v232, v195, v196
	v_mul_f32_e32 v232, 0.5, v232
	v_sub_f32_e32 v232, v232, v196
	ds_write_b32 v141, v232 offset:41984
	v_add_f32_e32 v231, v196, v197
	v_mul_f32_e32 v231, 0.5, v231
	v_sub_f32_e32 v231, v231, v197
	ds_write_b32 v141, v231 offset:43008
	v_add_f32_e32 v232, v197, v198
	v_mul_f32_e32 v232, 0.5, v232
	v_sub_f32_e32 v232, v232, v198
	ds_write_b32 v141, v232 offset:44032
	v_add_f32_e32 v231, v198, v199
	v_mul_f32_e32 v231, 0.5, v231
	v_sub_f32_e32 v231, v231, v199
	ds_write_b32 v141, v231 offset:45056
	v_add_f32_e32 v232, v199, v200
	v_mul_f32_e32 v232, 0.5, v232
	v_sub_f32_e32 v232, v232, v200
	ds_write_b32 v141, v232 offset:46080
	v_add_f32_e32 v231, v200, v201
	v_mul_f32_e32 v231, 0.5, v231
	v_sub_f32_e32 v231, v231, v201
	ds_write_b32 v141, v231 offset:47104
	v_add_f32_e32 v232, v201, v202
	v_mul_f32_e32 v232, 0.5, v232
	v_sub_f32_e32 v232, v232, v202
	ds_write_b32 v141, v232 offset:48128
	v_add_f32_e32 v231, v202, v203
	v_mul_f32_e32 v231, 0.5, v231
	v_sub_f32_e32 v231, v231, v203
	ds_write_b32 v141, v231 offset:49152
	v_add_f32_e32 v232, v203, v204
	v_mul_f32_e32 v232, 0.5, v232
	v_sub_f32_e32 v232, v232, v204
	ds_write_b32 v141, v232 offset:50176
	v_add_f32_e32 v231, v204, v205
	v_mul_f32_e32 v231, 0.5, v231
	v_sub_f32_e32 v231, v231, v205
	ds_write_b32 v141, v231 offset:51200
	v_add_f32_e32 v232, v205, v211
	v_mul_f32_e32 v232, 0.5, v232
	v_sub_f32_e32 v232, v232, v211
	ds_write_b32 v141, v232 offset:52224
	v_add_f32_e32 v231, v211, v212
	v_mul_f32_e32 v231, 0.5, v231
	v_sub_f32_e32 v231, v231, v212
	ds_write_b32 v141, v231 offset:53248
	v_add_f32_e32 v232, v212, v213
	v_mul_f32_e32 v232, 0.5, v232
	v_sub_f32_e32 v232, v232, v213
	ds_write_b32 v141, v232 offset:54272
	v_add_f32_e32 v231, v213, v214
	v_mul_f32_e32 v231, 0.5, v231
	v_sub_f32_e32 v231, v231, v214
	ds_write_b32 v141, v231 offset:55296
	v_add_f32_e32 v232, v214, v215
	v_mul_f32_e32 v232, 0.5, v232
	v_sub_f32_e32 v232, v232, v215
	ds_write_b32 v141, v232 offset:56320
	s_branch .LBB0_816
